# gate-up: row-statistics loads issued in the last K iteration (before its last DMAs), epilogue waits vmcnt(6) instead of draining; on top of v6
# baseline (speedup 1.0000x reference)
.LBB0_47:
	ds_read_b128 v[134:137], v130
	ds_read_b128 v[138:141], v130 offset:1024
	ds_read_b128 v[142:145], v130 offset:2048
	ds_read_b128 v[146:149], v130 offset:3072
	ds_read_b128 v[150:153], v131
	ds_read_b128 v[154:157], v131 offset:1024
	ds_read_b128 v[158:161], v131 offset:2048
	ds_read_b128 v[168:171], v131 offset:3072
	s_add_u32 s30, s60, 0xfffc0080
	s_addc_u32 s31, s61, -1
	s_cmp_eq_u32 s21, 12
	s_cselect_b32 s63, s1, s31
	s_cselect_b32 s62, s45, s30
	s_cselect_b32 s37, s53, s49
	s_cselect_b32 s36, s55, s23
	s_mov_b32 m0, s70
	v_lshl_add_u64 v[200:201], s[60:61], 0, v[164:165]
	ds_read_b128 v[172:175], v187
	ds_read_b128 v[176:179], v187 offset:1024
	ds_read_b128 v[180:183], v187 offset:2048
	ds_read_b128 v[188:191], v187 offset:3072
	ds_read_b128 v[192:195], v187 offset:4096
	ds_read_b128 v[196:199], v187 offset:5120
	ds_read_b128 v[210:213], v187 offset:6144
	ds_read_b128 v[214:217], v187 offset:7168
	global_load_lds_dwordx4 v[200:201], off
	v_lshl_add_u64 v[200:201], s[60:61], 0, v[166:167]
	s_mov_b32 m0, s71
	s_nop 0
	global_load_lds_dwordx4 v[200:201], off
	s_waitcnt vmcnt(8)
	s_waitcnt lgkmcnt(0)
	s_barrier
	s_setprio 1
	s_waitcnt lgkmcnt(0)
	v_mfma_f32_16x16x32_bf16 v[122:125], v[134:137], v[172:175], v[122:125]
	v_mfma_f32_16x16x32_bf16 v[114:117], v[142:145], v[172:175], v[114:117]
	v_mfma_f32_16x16x32_bf16 v[106:109], v[134:137], v[180:183], v[106:109]
	v_mfma_f32_16x16x32_bf16 v[98:101], v[142:145], v[180:183], v[98:101]
	v_mfma_f32_16x16x32_bf16 v[90:93], v[134:137], v[192:195], v[90:93]
	v_mfma_f32_16x16x32_bf16 v[82:85], v[142:145], v[192:195], v[82:85]
	v_mfma_f32_16x16x32_bf16 v[74:77], v[134:137], v[210:213], v[74:77]
	v_mfma_f32_16x16x32_bf16 v[66:69], v[142:145], v[210:213], v[66:69]
	v_mfma_f32_16x16x32_bf16 v[122:125], v[138:141], v[176:179], v[122:125]
	v_mfma_f32_16x16x32_bf16 v[114:117], v[146:149], v[176:179], v[114:117]
	v_mfma_f32_16x16x32_bf16 v[106:109], v[138:141], v[188:191], v[106:109]
	v_mfma_f32_16x16x32_bf16 v[98:101], v[146:149], v[188:191], v[98:101]
	v_mfma_f32_16x16x32_bf16 v[90:93], v[138:141], v[196:199], v[90:93]
	v_mfma_f32_16x16x32_bf16 v[82:85], v[146:149], v[196:199], v[82:85]
	v_mfma_f32_16x16x32_bf16 v[74:77], v[138:141], v[214:217], v[74:77]
	v_mfma_f32_16x16x32_bf16 v[66:69], v[146:149], v[214:217], v[66:69]
	s_setprio 0
	s_setprio 1
	v_mfma_f32_16x16x32_bf16 v[126:129], v[150:153], v[172:175], v[126:129]
	v_mfma_f32_16x16x32_bf16 v[118:121], v[158:161], v[172:175], v[118:121]
	v_mfma_f32_16x16x32_bf16 v[110:113], v[150:153], v[180:183], v[110:113]
	v_mfma_f32_16x16x32_bf16 v[102:105], v[158:161], v[180:183], v[102:105]
	v_mfma_f32_16x16x32_bf16 v[94:97], v[150:153], v[192:195], v[94:97]
	v_mfma_f32_16x16x32_bf16 v[86:89], v[158:161], v[192:195], v[86:89]
	v_mfma_f32_16x16x32_bf16 v[78:81], v[150:153], v[210:213], v[78:81]
	v_mfma_f32_16x16x32_bf16 v[70:73], v[158:161], v[210:213], v[70:73]
	v_mfma_f32_16x16x32_bf16 v[126:129], v[154:157], v[176:179], v[126:129]
	v_mfma_f32_16x16x32_bf16 v[118:121], v[168:171], v[176:179], v[118:121]
	v_mfma_f32_16x16x32_bf16 v[110:113], v[154:157], v[188:191], v[110:113]
	v_mfma_f32_16x16x32_bf16 v[102:105], v[168:171], v[188:191], v[102:105]
	v_mfma_f32_16x16x32_bf16 v[94:97], v[154:157], v[196:199], v[94:97]
	v_mfma_f32_16x16x32_bf16 v[86:89], v[168:171], v[196:199], v[86:89]
	v_mfma_f32_16x16x32_bf16 v[78:81], v[154:157], v[214:217], v[78:81]
	v_mfma_f32_16x16x32_bf16 v[70:73], v[168:171], v[214:217], v[70:73]
	s_setprio 0
	s_barrier
	s_mov_b32 m0, s93
	v_lshl_add_u64 v[200:201], s[36:37], 0, v[0:1]
	s_add_u32 s30, s36, 0x40000
	ds_read_b128 v[172:175], v187 offset:16384
	ds_read_b128 v[176:179], v187 offset:17408
	ds_read_b128 v[180:183], v187 offset:18432
	ds_read_b128 v[188:191], v187 offset:19456
	ds_read_b128 v[192:195], v187 offset:20480
	ds_read_b128 v[196:199], v187 offset:21504
	ds_read_b128 v[210:213], v187 offset:22528
	ds_read_b128 v[214:217], v187 offset:23552
	global_load_lds_dwordx4 v[200:201], off
	v_lshl_add_u64 v[204:205], s[36:37], 0, v[162:163]
	s_mov_b32 m0, s94
	s_addc_u32 s31, s37, 0
	global_load_lds_dwordx4 v[204:205], off
	v_lshl_add_u64 v[208:209], s[30:31], 0, v[0:1]
	s_mov_b32 m0, s95
	v_lshl_add_u64 v[218:219], s[62:63], 0, v[162:163]
	global_load_lds_dwordx4 v[208:209], off
	v_lshl_add_u64 v[208:209], s[30:31], 0, v[162:163]
	s_mov_b32 m0, s96
	s_nop 0
	global_load_lds_dwordx4 v[208:209], off
	v_lshl_add_u64 v[208:209], s[62:63], 0, v[0:1]
	s_mov_b32 m0, s43
	s_nop 0
	global_load_lds_dwordx4 v[208:209], off
	s_mov_b32 m0, s64
	s_nop 0
	global_load_lds_dwordx4 v[218:219], off
	s_waitcnt vmcnt(8)
	s_waitcnt lgkmcnt(0)
	s_barrier
; __device__ __forceinline__ void rstd8(const float* SS, int row0, int fq, float (&r)[2][4]) {
;     f32x4 v[2][4];
; #pragma unroll
;     for (int ai = 0; ai < 2; ++ai)
; #pragma unroll
;         for (int m = 0; m < 4; ++m) v[ai][m] = *(const f32x4*)(SS + (size_t)(row0 + ai * 128 + m * 16) * 16 + 4 * fq);
	s_setprio 1
	s_waitcnt lgkmcnt(0)
	v_mfma_f32_16x16x32_bf16 v[58:61], v[134:137], v[172:175], v[58:61]
	v_mfma_f32_16x16x32_bf16 v[50:53], v[142:145], v[172:175], v[50:53]
	v_mfma_f32_16x16x32_bf16 v[42:45], v[134:137], v[180:183], v[42:45]
	v_mfma_f32_16x16x32_bf16 v[34:37], v[142:145], v[180:183], v[34:37]
	v_mfma_f32_16x16x32_bf16 v[26:29], v[134:137], v[192:195], v[26:29]
	v_mfma_f32_16x16x32_bf16 v[18:21], v[142:145], v[192:195], v[18:21]
	v_mfma_f32_16x16x32_bf16 v[10:13], v[134:137], v[210:213], v[10:13]
	v_mfma_f32_16x16x32_bf16 v[2:5], v[142:145], v[210:213], v[2:5]
	v_mfma_f32_16x16x32_bf16 v[58:61], v[138:141], v[176:179], v[58:61]
	v_mfma_f32_16x16x32_bf16 v[50:53], v[146:149], v[176:179], v[50:53]
	v_mfma_f32_16x16x32_bf16 v[42:45], v[138:141], v[188:191], v[42:45]
	v_mfma_f32_16x16x32_bf16 v[34:37], v[146:149], v[188:191], v[34:37]
	v_mfma_f32_16x16x32_bf16 v[26:29], v[138:141], v[196:199], v[26:29]
	v_mfma_f32_16x16x32_bf16 v[18:21], v[146:149], v[196:199], v[18:21]
	v_mfma_f32_16x16x32_bf16 v[10:13], v[138:141], v[214:217], v[10:13]
	v_mfma_f32_16x16x32_bf16 v[2:5], v[146:149], v[214:217], v[2:5]
	s_setprio 0
	s_setprio 1
	v_mfma_f32_16x16x32_bf16 v[62:65], v[150:153], v[172:175], v[62:65]
	v_mfma_f32_16x16x32_bf16 v[54:57], v[158:161], v[172:175], v[54:57]
	v_mfma_f32_16x16x32_bf16 v[46:49], v[150:153], v[180:183], v[46:49]
	v_mfma_f32_16x16x32_bf16 v[38:41], v[158:161], v[180:183], v[38:41]
	v_mfma_f32_16x16x32_bf16 v[30:33], v[150:153], v[192:195], v[30:33]
	v_mfma_f32_16x16x32_bf16 v[22:25], v[158:161], v[192:195], v[22:25]
	v_mfma_f32_16x16x32_bf16 v[14:17], v[150:153], v[210:213], v[14:17]
	v_mfma_f32_16x16x32_bf16 v[6:9], v[158:161], v[210:213], v[6:9]
	v_mfma_f32_16x16x32_bf16 v[62:65], v[154:157], v[176:179], v[62:65]
	v_mfma_f32_16x16x32_bf16 v[54:57], v[168:171], v[176:179], v[54:57]
	v_mfma_f32_16x16x32_bf16 v[46:49], v[154:157], v[188:191], v[46:49]
	v_mfma_f32_16x16x32_bf16 v[38:41], v[168:171], v[188:191], v[38:41]
	v_mfma_f32_16x16x32_bf16 v[30:33], v[154:157], v[196:199], v[30:33]
	v_mfma_f32_16x16x32_bf16 v[22:25], v[168:171], v[196:199], v[22:25]
	v_mfma_f32_16x16x32_bf16 v[14:17], v[154:157], v[214:217], v[14:17]
	v_mfma_f32_16x16x32_bf16 v[6:9], v[168:171], v[214:217], v[6:9]
	s_setprio 0
	s_barrier
	ds_read_b128 v[134:137], v132
	ds_read_b128 v[138:141], v132 offset:1024
	ds_read_b128 v[142:145], v132 offset:2048
	ds_read_b128 v[146:149], v132 offset:3072
	ds_read_b128 v[150:153], v133
	ds_read_b128 v[154:157], v133 offset:1024
	ds_read_b128 v[158:161], v133 offset:2048
	ds_read_b128 v[168:171], v133 offset:3072
	s_add_u32 s30, s62, 0x40000
	s_addc_u32 s31, s63, 0
	s_mov_b32 m0, s65
	v_lshl_add_u64 v[220:221], s[30:31], 0, v[0:1]
	ds_read_b128 v[172:175], v187 offset:32768
	ds_read_b128 v[176:179], v187 offset:33792
	ds_read_b128 v[180:183], v187 offset:34816
	ds_read_b128 v[188:191], v187 offset:35840
	ds_read_b128 v[192:195], v187 offset:36864
	ds_read_b128 v[196:199], v187 offset:37888
	ds_read_b128 v[210:213], v187 offset:38912
	ds_read_b128 v[214:217], v187 offset:39936
	global_load_lds_dwordx4 v[220:221], off
	v_lshl_add_u64 v[220:221], s[30:31], 0, v[162:163]
	s_mov_b32 m0, s66
	s_nop 0
	global_load_lds_dwordx4 v[220:221], off
	s_waitcnt vmcnt(8)
	s_waitcnt lgkmcnt(0)
	s_barrier
	s_setprio 1
	s_waitcnt lgkmcnt(0)
	v_mfma_f32_16x16x32_bf16 v[122:125], v[134:137], v[172:175], v[122:125]
	v_mfma_f32_16x16x32_bf16 v[114:117], v[142:145], v[172:175], v[114:117]
	v_mfma_f32_16x16x32_bf16 v[106:109], v[134:137], v[180:183], v[106:109]
	v_mfma_f32_16x16x32_bf16 v[98:101], v[142:145], v[180:183], v[98:101]
	v_mfma_f32_16x16x32_bf16 v[90:93], v[134:137], v[192:195], v[90:93]
	v_mfma_f32_16x16x32_bf16 v[82:85], v[142:145], v[192:195], v[82:85]
	v_mfma_f32_16x16x32_bf16 v[74:77], v[134:137], v[210:213], v[74:77]
	v_mfma_f32_16x16x32_bf16 v[66:69], v[142:145], v[210:213], v[66:69]
	v_mfma_f32_16x16x32_bf16 v[122:125], v[138:141], v[176:179], v[122:125]
	v_mfma_f32_16x16x32_bf16 v[114:117], v[146:149], v[176:179], v[114:117]
	v_mfma_f32_16x16x32_bf16 v[106:109], v[138:141], v[188:191], v[106:109]
	v_mfma_f32_16x16x32_bf16 v[98:101], v[146:149], v[188:191], v[98:101]
	v_mfma_f32_16x16x32_bf16 v[90:93], v[138:141], v[196:199], v[90:93]
	v_mfma_f32_16x16x32_bf16 v[82:85], v[146:149], v[196:199], v[82:85]
	v_mfma_f32_16x16x32_bf16 v[74:77], v[138:141], v[214:217], v[74:77]
	v_mfma_f32_16x16x32_bf16 v[66:69], v[146:149], v[214:217], v[66:69]
	s_setprio 0
	s_setprio 1
	v_mfma_f32_16x16x32_bf16 v[126:129], v[150:153], v[172:175], v[126:129]
	v_mfma_f32_16x16x32_bf16 v[118:121], v[158:161], v[172:175], v[118:121]
	v_mfma_f32_16x16x32_bf16 v[110:113], v[150:153], v[180:183], v[110:113]
	v_mfma_f32_16x16x32_bf16 v[102:105], v[158:161], v[180:183], v[102:105]
	v_mfma_f32_16x16x32_bf16 v[94:97], v[150:153], v[192:195], v[94:97]
	v_mfma_f32_16x16x32_bf16 v[86:89], v[158:161], v[192:195], v[86:89]
	v_mfma_f32_16x16x32_bf16 v[78:81], v[150:153], v[210:213], v[78:81]
	v_mfma_f32_16x16x32_bf16 v[70:73], v[158:161], v[210:213], v[70:73]
	v_mfma_f32_16x16x32_bf16 v[126:129], v[154:157], v[176:179], v[126:129]
	v_mfma_f32_16x16x32_bf16 v[118:121], v[168:171], v[176:179], v[118:121]
	v_mfma_f32_16x16x32_bf16 v[110:113], v[154:157], v[188:191], v[110:113]
	v_mfma_f32_16x16x32_bf16 v[102:105], v[168:171], v[188:191], v[102:105]
	v_mfma_f32_16x16x32_bf16 v[94:97], v[154:157], v[196:199], v[94:97]
	v_mfma_f32_16x16x32_bf16 v[86:89], v[168:171], v[196:199], v[86:89]
	v_mfma_f32_16x16x32_bf16 v[78:81], v[154:157], v[214:217], v[78:81]
	v_mfma_f32_16x16x32_bf16 v[70:73], v[168:171], v[214:217], v[70:73]
	s_setprio 0
	s_barrier
	s_cmp_eq_u32 s21, 12
	s_cbranch_scc0 .Lgu_noss
	v_lshl_add_u32 v250, s0, 8, v184
	v_add_u32_e32 v250, s68, v250
	v_lshlrev_b32_e32 v251, 4, v185
	v_lshl_add_u32 v250, v250, 6, v251
	global_load_dwordx4 v[222:225], v250, s[46:47]
	global_load_dwordx4 v[226:229], v250, s[46:47] offset:1024
	global_load_dwordx4 v[230:233], v250, s[46:47] offset:2048
	global_load_dwordx4 v[234:237], v250, s[46:47] offset:3072
	v_add_u32_e32 v250, 0x2000, v250
	global_load_dwordx4 v[238:241], v250, s[46:47]
	global_load_dwordx4 v[242:245], v250, s[46:47] offset:1024
	global_load_dwordx4 v[246:249], v250, s[46:47] offset:2048
	global_load_dwordx4 v[130:133], v250, s[46:47] offset:3072
; __device__ __forceinline__ void rstd8(const float* SS, int row0, int fq, float (&r)[2][4]) {
;     f32x4 v[2][4];
; #pragma unroll
;     for (int ai = 0; ai < 2; ++ai)
; #pragma unroll
;         for (int m = 0; m < 4; ++m) v[ai][m] = *(const f32x4*)(SS + (size_t)(row0 + ai * 128 + m * 16) * 16 + 4 * fq);
; #pragma unroll
;     for (int ai = 0; ai < 2; ++ai)
; #pragma unroll
;         for (int m = 0; m < 4; ++m) { float s = (v[ai][m][0] + v[ai][m][1]) + (v[ai][m][2] + v[ai][m][3]); s += __shfl_xor(s, 16); s += __shfl_xor(s, 32); r[ai][m] = rsqrtf(s * (1.0f / 1024.0f) + 1e-6f); }
; }
.Lgu_noss:
	s_mov_b32 m0, s97
	v_lshl_add_u64 v[200:201], v[200:201], 0, s[26:27]
	s_add_u32 s30, s36, 0x40080
	ds_read_b128 v[172:175], v187 offset:49152
	ds_read_b128 v[176:179], v187 offset:50176
	ds_read_b128 v[180:183], v187 offset:51200
	ds_read_b128 v[188:191], v187 offset:52224
	ds_read_b128 v[192:195], v187 offset:53248
	ds_read_b128 v[196:199], v187 offset:54272
	ds_read_b128 v[210:213], v187 offset:55296
	ds_read_b128 v[214:217], v187 offset:56320
	global_load_lds_dwordx4 v[200:201], off
	v_lshl_add_u64 v[200:201], v[204:205], 0, s[26:27]
	s_mov_b32 m0, vcc_lo
	s_addc_u32 s31, s37, 0
	global_load_lds_dwordx4 v[200:201], off
	v_lshl_add_u64 v[200:201], s[30:31], 0, v[0:1]
	s_mov_b32 m0, vcc_hi
	s_nop 0
	global_load_lds_dwordx4 v[200:201], off
	v_lshl_add_u64 v[200:201], s[30:31], 0, v[162:163]
	s_mov_b32 m0, s48
	s_nop 0
	global_load_lds_dwordx4 v[200:201], off
	v_lshl_add_u64 v[200:201], v[208:209], 0, s[26:27]
	s_mov_b32 m0, s69
	s_nop 0
	global_load_lds_dwordx4 v[200:201], off
	v_lshl_add_u64 v[200:201], v[218:219], 0, s[26:27]
	s_mov_b32 m0, s72
	s_nop 0
	global_load_lds_dwordx4 v[200:201], off
	s_cmp_eq_u32 s21, 12
	s_cbranch_scc1 .Lgu_w16
	s_waitcnt vmcnt(8)
	s_branch .Lgu_wj
.Lgu_w16:
	s_waitcnt vmcnt(16)
.Lgu_wj:
	s_waitcnt lgkmcnt(0)
	s_barrier
	s_setprio 1
	s_waitcnt lgkmcnt(0)
	v_mfma_f32_16x16x32_bf16 v[58:61], v[134:137], v[172:175], v[58:61]
	v_mfma_f32_16x16x32_bf16 v[50:53], v[142:145], v[172:175], v[50:53]
	v_mfma_f32_16x16x32_bf16 v[42:45], v[134:137], v[180:183], v[42:45]
	v_mfma_f32_16x16x32_bf16 v[34:37], v[142:145], v[180:183], v[34:37]
	v_mfma_f32_16x16x32_bf16 v[26:29], v[134:137], v[192:195], v[26:29]
	v_mfma_f32_16x16x32_bf16 v[18:21], v[142:145], v[192:195], v[18:21]
	v_mfma_f32_16x16x32_bf16 v[10:13], v[134:137], v[210:213], v[10:13]
	v_mfma_f32_16x16x32_bf16 v[2:5], v[142:145], v[210:213], v[2:5]
	v_mfma_f32_16x16x32_bf16 v[58:61], v[138:141], v[176:179], v[58:61]
	v_mfma_f32_16x16x32_bf16 v[50:53], v[146:149], v[176:179], v[50:53]
	v_mfma_f32_16x16x32_bf16 v[42:45], v[138:141], v[188:191], v[42:45]
	v_mfma_f32_16x16x32_bf16 v[34:37], v[146:149], v[188:191], v[34:37]
	v_mfma_f32_16x16x32_bf16 v[26:29], v[138:141], v[196:199], v[26:29]
	v_mfma_f32_16x16x32_bf16 v[18:21], v[146:149], v[196:199], v[18:21]
	v_mfma_f32_16x16x32_bf16 v[10:13], v[138:141], v[214:217], v[10:13]
	v_mfma_f32_16x16x32_bf16 v[2:5], v[146:149], v[214:217], v[2:5]
	s_setprio 0
	s_setprio 1
	v_mfma_f32_16x16x32_bf16 v[62:65], v[150:153], v[172:175], v[62:65]
	v_mfma_f32_16x16x32_bf16 v[54:57], v[158:161], v[172:175], v[54:57]
	v_mfma_f32_16x16x32_bf16 v[46:49], v[150:153], v[180:183], v[46:49]
	v_mfma_f32_16x16x32_bf16 v[38:41], v[158:161], v[180:183], v[38:41]
	v_mfma_f32_16x16x32_bf16 v[30:33], v[150:153], v[192:195], v[30:33]
	v_mfma_f32_16x16x32_bf16 v[22:25], v[158:161], v[192:195], v[22:25]
	v_mfma_f32_16x16x32_bf16 v[14:17], v[150:153], v[210:213], v[14:17]
	v_mfma_f32_16x16x32_bf16 v[6:9], v[158:161], v[210:213], v[6:9]
	v_mfma_f32_16x16x32_bf16 v[62:65], v[154:157], v[176:179], v[62:65]
	v_mfma_f32_16x16x32_bf16 v[54:57], v[168:171], v[176:179], v[54:57]
	v_mfma_f32_16x16x32_bf16 v[46:49], v[154:157], v[188:191], v[46:49]
	v_mfma_f32_16x16x32_bf16 v[38:41], v[168:171], v[188:191], v[38:41]
	v_mfma_f32_16x16x32_bf16 v[30:33], v[154:157], v[196:199], v[30:33]
	v_mfma_f32_16x16x32_bf16 v[22:25], v[168:171], v[196:199], v[22:25]
	v_mfma_f32_16x16x32_bf16 v[14:17], v[154:157], v[214:217], v[14:17]
	v_mfma_f32_16x16x32_bf16 v[6:9], v[168:171], v[214:217], v[6:9]
	s_setprio 0
	s_barrier
	s_add_i32 s21, s21, 2
	s_add_u32 s60, s60, 0x100
	s_addc_u32 s61, s61, 0
	s_add_u32 s23, s23, 0x100
	s_addc_u32 s49, s49, 0
	s_cmp_gt_u32 s21, 13
	s_cbranch_scc0 .LBB0_47
	s_and_b64 vcc, exec, s[50:51]
	s_cbranch_vccz .LBB0_50
	s_barrier
.LBB0_50:
	s_lshl_b32 s0, s0, 8
	s_add_i32 s0, s0, s68
	v_add_u32_e32 v168, s0, v184
	v_xor_b32_e32 v170, 16, v203
	v_xor_b32_e32 v171, 32, v203
	v_lshlrev_b32_e32 v170, 2, v170
	v_lshlrev_b32_e32 v171, 2, v171
	s_movk_i32 s21, 0x1600
	v_readlane_b32 s30, v253, 13
	v_readlane_b32 s31, v253, 14
	s_lshl_b32 s0, s44, 8
	s_add_i32 s0, s0, s24
	v_mul_lo_u32 v172, v168, s21
	v_lshl_add_u32 v173, v185, 4, s0
	v_add_u32_e32 v172, v172, v173
	s_mov_b32 s0, 0x3a800000
	v_mov_b32_e32 v173, 0x358637bd
	s_waitcnt vmcnt(6)
	v_add_f32_e32 v222, v222, v223
	v_add_f32_e32 v224, v224, v225
	v_add_f32_e32 v226, v226, v227
	v_add_f32_e32 v228, v228, v229
	v_add_f32_e32 v230, v230, v231
	v_add_f32_e32 v232, v232, v233
	v_add_f32_e32 v234, v234, v235
	v_add_f32_e32 v236, v236, v237
	v_add_f32_e32 v238, v238, v239
	v_add_f32_e32 v240, v240, v241
	v_add_f32_e32 v242, v242, v243
	v_add_f32_e32 v244, v244, v245
	v_add_f32_e32 v246, v246, v247
	v_add_f32_e32 v248, v248, v249
	v_add_f32_e32 v130, v130, v131
	v_add_f32_e32 v132, v132, v133
	v_add_f32_e32 v222, v222, v224
	v_add_f32_e32 v226, v226, v228
	v_add_f32_e32 v230, v230, v232
	v_add_f32_e32 v234, v234, v236
	v_add_f32_e32 v238, v238, v240
	v_add_f32_e32 v242, v242, v244
	v_add_f32_e32 v246, v246, v248
	v_add_f32_e32 v130, v130, v132
	ds_bpermute_b32 v223, v170, v222
	ds_bpermute_b32 v227, v170, v226
	ds_bpermute_b32 v231, v170, v230
	ds_bpermute_b32 v235, v170, v234
	ds_bpermute_b32 v239, v170, v238
	ds_bpermute_b32 v243, v170, v242
	ds_bpermute_b32 v247, v170, v246
	ds_bpermute_b32 v131, v170, v130
	s_waitcnt lgkmcnt(0)
; __device__ __forceinline__ float sigm(float x) { return __builtin_amdgcn_rcpf(1.0f + __expf(-x)); }
; __device__ __forceinline__ u32x4 pack8(f32x4 a, f32x4 b) { u32x4 w; w.x = cvt_pk_bf16(a[0], a[1]); w.y = cvt_pk_bf16(a[2], a[3]); w.z = cvt_pk_bf16(b[0], b[1]); w.w = cvt_pk_bf16(b[2], b[3]); return w; }
; __device__ __forceinline__ void rstd8(const float* SS, int row0, int fq, float (&r)[2][4]) {
;     ...
;         for (int m = 0; m < 4; ++m) { float s = (v[ai][m][0] + v[ai][m][1]) + (v[ai][m][2] + v[ai][m][3]); s += __shfl_xor(s, 16); s += __shfl_xor(s, 32); r[ai][m] = rsqrtf(s * (1.0f / 1024.0f) + 1e-6f); }
; }
;     __device__ __forceinline__ void operator()(const f32x4 (&acc)[2][2][4][2], const Unit& u, int wr, int wc, int fr_, int fq_) const {
;     ...
; #pragma unroll
;         for (int ai = 0; ai < 2; ++ai)
; #pragma unroll
;             for (int m = 0; m < 4; ++m) {
;                 const int row = u.pm * 256 + ai * 128 + wr * 64 + m * 16 + fr;
;                 const float rstd = rs8[ai][m];
;                 f32x4 o[2];
; #pragma unroll
;                 for (int n = 0; n < 2; ++n) { const f32x4 g = acc[ai][0][m][n] * rstd, up = acc[ai][1][m][n] * rstd;
; #pragma unroll
;                     for (int i = 0; i < 4; ++i) o[n][i] = g[i] * sigm(g[i]) * up[i]; }
;                 *(u32x4*)(ACT + (size_t)row * DFF + 128 * u.pn + 32 * wc + 8 * fq) = pack8(o[0], o[1]);
	v_add_f32_e32 v222, v222, v223
	v_add_f32_e32 v226, v226, v227
	v_add_f32_e32 v230, v230, v231
	v_add_f32_e32 v234, v234, v235
	v_add_f32_e32 v238, v238, v239
	v_add_f32_e32 v242, v242, v243
	v_add_f32_e32 v246, v246, v247
	v_add_f32_e32 v130, v130, v131
	ds_bpermute_b32 v223, v171, v222
	ds_bpermute_b32 v227, v171, v226
	ds_bpermute_b32 v231, v171, v230
	ds_bpermute_b32 v235, v171, v234
	ds_bpermute_b32 v239, v171, v238
	ds_bpermute_b32 v243, v171, v242
	ds_bpermute_b32 v247, v171, v246
	ds_bpermute_b32 v131, v171, v130
	s_waitcnt lgkmcnt(0)
	v_add_f32_e32 v222, v222, v223
	v_add_f32_e32 v226, v226, v227
	v_add_f32_e32 v230, v230, v231
	v_add_f32_e32 v234, v234, v235
	v_add_f32_e32 v238, v238, v239
	v_add_f32_e32 v242, v242, v243
	v_add_f32_e32 v246, v246, v247
	v_add_f32_e32 v130, v130, v131
	v_fma_f32 v222, v222, s0, v173
	v_fma_f32 v226, v226, s0, v173
	v_fma_f32 v230, v230, s0, v173
	v_fma_f32 v234, v234, s0, v173
	v_fma_f32 v238, v238, s0, v173
	v_fma_f32 v242, v242, s0, v173
	v_fma_f32 v246, v246, s0, v173
	v_fma_f32 v130, v130, s0, v173
	v_rsq_f32_e32 v223, v222
	v_rsq_f32_e32 v227, v226
	v_rsq_f32_e32 v231, v230
	v_rsq_f32_e32 v235, v234
	v_rsq_f32_e32 v239, v238
	v_rsq_f32_e32 v243, v242
	v_rsq_f32_e32 v247, v246
	v_rsq_f32_e32 v131, v130
	v_mul_f32_e32 v223, 0xbfb8aa3b, v223
	v_mul_f32_e32 v227, 0xbfb8aa3b, v227
	v_mul_f32_e32 v231, 0xbfb8aa3b, v231
	v_mul_f32_e32 v235, 0xbfb8aa3b, v235
	v_mul_f32_e32 v239, 0xbfb8aa3b, v239
	v_mul_f32_e32 v243, 0xbfb8aa3b, v243
	v_mul_f32_e32 v247, 0xbfb8aa3b, v247
	v_mul_f32_e32 v131, 0xbfb8aa3b, v131
	v_mul_f32_e32 v126, v122, v126
	v_mul_f32_e32 v127, v123, v127
	v_mul_f32_e32 v128, v124, v128
	v_mul_f32_e32 v129, v125, v129
	v_mul_f32_e32 v118, v114, v118
	v_mul_f32_e32 v119, v115, v119
	v_mul_f32_e32 v120, v116, v120
	v_mul_f32_e32 v121, v117, v121
	v_mul_f32_e32 v122, v223, v122
	v_mul_f32_e32 v123, v223, v123
	v_mul_f32_e32 v124, v223, v124
	v_mul_f32_e32 v125, v223, v125
	v_mul_f32_e32 v114, v223, v114
	v_mul_f32_e32 v115, v223, v115
	v_mul_f32_e32 v116, v223, v116
	v_mul_f32_e32 v117, v223, v117
	v_exp_f32_e32 v122, v122
	v_exp_f32_e32 v123, v123
	v_exp_f32_e32 v124, v124
	v_exp_f32_e32 v125, v125
	v_exp_f32_e32 v114, v114
	v_exp_f32_e32 v115, v115
	v_exp_f32_e32 v116, v116
	v_exp_f32_e32 v117, v117
	v_fma_f32 v122, v122, v222, v222
	v_fma_f32 v123, v123, v222, v222
	v_fma_f32 v124, v124, v222, v222
	v_fma_f32 v125, v125, v222, v222
	v_fma_f32 v114, v114, v222, v222
	v_fma_f32 v115, v115, v222, v222
	v_fma_f32 v116, v116, v222, v222
	v_fma_f32 v117, v117, v222, v222
	v_rcp_f32_e32 v122, v122
	v_rcp_f32_e32 v123, v123
	v_rcp_f32_e32 v124, v124
	v_rcp_f32_e32 v125, v125
	v_rcp_f32_e32 v114, v114
	v_rcp_f32_e32 v115, v115
	v_rcp_f32_e32 v116, v116
	v_rcp_f32_e32 v117, v117
	v_mul_f32_e32 v126, v126, v122
	v_mul_f32_e32 v127, v127, v123
	v_mul_f32_e32 v128, v128, v124
	v_mul_f32_e32 v129, v129, v125
	v_mul_f32_e32 v118, v118, v114
	v_mul_f32_e32 v119, v119, v115
	v_mul_f32_e32 v120, v120, v116
	v_mul_f32_e32 v121, v121, v117
	v_cvt_pk_bf16_f32 v122, v126, v127
	v_cvt_pk_bf16_f32 v123, v128, v129
	v_cvt_pk_bf16_f32 v124, v118, v119
	v_cvt_pk_bf16_f32 v125, v120, v121
	global_store_dwordx4 v172, v[122:125], s[30:31]
	v_add_u32_e32 v172, 0x16000, v172
	v_mul_f32_e32 v110, v106, v110
	v_mul_f32_e32 v111, v107, v111
	v_mul_f32_e32 v112, v108, v112
	v_mul_f32_e32 v113, v109, v113
	v_mul_f32_e32 v102, v98, v102
	v_mul_f32_e32 v103, v99, v103
	v_mul_f32_e32 v104, v100, v104
	v_mul_f32_e32 v105, v101, v105
	v_mul_f32_e32 v106, v227, v106
	v_mul_f32_e32 v107, v227, v107
	v_mul_f32_e32 v108, v227, v108
	v_mul_f32_e32 v109, v227, v109
	v_mul_f32_e32 v98, v227, v98
	v_mul_f32_e32 v99, v227, v99
	v_mul_f32_e32 v100, v227, v100
	v_mul_f32_e32 v101, v227, v101
	v_exp_f32_e32 v106, v106
	v_exp_f32_e32 v107, v107
	v_exp_f32_e32 v108, v108
	v_exp_f32_e32 v109, v109
	v_exp_f32_e32 v98, v98
	v_exp_f32_e32 v99, v99
	v_exp_f32_e32 v100, v100
	v_exp_f32_e32 v101, v101
	v_fma_f32 v106, v106, v226, v226
	v_fma_f32 v107, v107, v226, v226
	v_fma_f32 v108, v108, v226, v226
	v_fma_f32 v109, v109, v226, v226
	v_fma_f32 v98, v98, v226, v226
	v_fma_f32 v99, v99, v226, v226
	v_fma_f32 v100, v100, v226, v226
	v_fma_f32 v101, v101, v226, v226
	v_rcp_f32_e32 v106, v106
	v_rcp_f32_e32 v107, v107
	v_rcp_f32_e32 v108, v108
	v_rcp_f32_e32 v109, v109
	v_rcp_f32_e32 v98, v98
	v_rcp_f32_e32 v99, v99
	v_rcp_f32_e32 v100, v100
	v_rcp_f32_e32 v101, v101
	v_mul_f32_e32 v110, v110, v106
	v_mul_f32_e32 v111, v111, v107
	v_mul_f32_e32 v112, v112, v108
	v_mul_f32_e32 v113, v113, v109
	v_mul_f32_e32 v102, v102, v98
	v_mul_f32_e32 v103, v103, v99
	v_mul_f32_e32 v104, v104, v100
	v_mul_f32_e32 v105, v105, v101
	v_cvt_pk_bf16_f32 v106, v110, v111
	v_cvt_pk_bf16_f32 v107, v112, v113
	v_cvt_pk_bf16_f32 v108, v102, v103
	v_cvt_pk_bf16_f32 v109, v104, v105
	global_store_dwordx4 v172, v[106:109], s[30:31]
	v_add_u32_e32 v172, 0x16000, v172
	v_mul_f32_e32 v94, v90, v94
	v_mul_f32_e32 v95, v91, v95
	v_mul_f32_e32 v96, v92, v96
	v_mul_f32_e32 v97, v93, v97
	v_mul_f32_e32 v86, v82, v86
	v_mul_f32_e32 v87, v83, v87
	v_mul_f32_e32 v88, v84, v88
	v_mul_f32_e32 v89, v85, v89
	v_mul_f32_e32 v90, v231, v90
	v_mul_f32_e32 v91, v231, v91
	v_mul_f32_e32 v92, v231, v92
	v_mul_f32_e32 v93, v231, v93
	v_mul_f32_e32 v82, v231, v82
	v_mul_f32_e32 v83, v231, v83
	v_mul_f32_e32 v84, v231, v84
	v_mul_f32_e32 v85, v231, v85
	v_exp_f32_e32 v90, v90
	v_exp_f32_e32 v91, v91
	v_exp_f32_e32 v92, v92
	v_exp_f32_e32 v93, v93
	v_exp_f32_e32 v82, v82
	v_exp_f32_e32 v83, v83
	v_exp_f32_e32 v84, v84
	v_exp_f32_e32 v85, v85
	v_fma_f32 v90, v90, v230, v230
	v_fma_f32 v91, v91, v230, v230
; __device__ __forceinline__ float sigm(float x) { return __builtin_amdgcn_rcpf(1.0f + __expf(-x)); }
; __device__ __forceinline__ u32x4 pack8(f32x4 a, f32x4 b) { u32x4 w; w.x = cvt_pk_bf16(a[0], a[1]); w.y = cvt_pk_bf16(a[2], a[3]); w.z = cvt_pk_bf16(b[0], b[1]); w.w = cvt_pk_bf16(b[2], b[3]); return w; }
;     __device__ __forceinline__ void operator()(const f32x4 (&acc)[2][2][4][2], const Unit& u, int wr, int wc, int fr_, int fq_) const {
;     ...
; #pragma unroll
;         for (int ai = 0; ai < 2; ++ai)
; #pragma unroll
;             for (int m = 0; m < 4; ++m) {
;                 const int row = u.pm * 256 + ai * 128 + wr * 64 + m * 16 + fr;
;                 const float rstd = rs8[ai][m];
;                 f32x4 o[2];
; #pragma unroll
;                 for (int n = 0; n < 2; ++n) { const f32x4 g = acc[ai][0][m][n] * rstd, up = acc[ai][1][m][n] * rstd;
; #pragma unroll
;                     for (int i = 0; i < 4; ++i) o[n][i] = g[i] * sigm(g[i]) * up[i]; }
;                 *(u32x4*)(ACT + (size_t)row * DFF + 128 * u.pn + 32 * wc + 8 * fq) = pack8(o[0], o[1]);
	v_fma_f32 v92, v92, v230, v230
	v_fma_f32 v93, v93, v230, v230
	v_fma_f32 v82, v82, v230, v230
	v_fma_f32 v83, v83, v230, v230
	v_fma_f32 v84, v84, v230, v230
	v_fma_f32 v85, v85, v230, v230
	v_rcp_f32_e32 v90, v90
	v_rcp_f32_e32 v91, v91
	v_rcp_f32_e32 v92, v92
	v_rcp_f32_e32 v93, v93
	v_rcp_f32_e32 v82, v82
	v_rcp_f32_e32 v83, v83
	v_rcp_f32_e32 v84, v84
	v_rcp_f32_e32 v85, v85
	v_mul_f32_e32 v94, v94, v90
	v_mul_f32_e32 v95, v95, v91
	v_mul_f32_e32 v96, v96, v92
	v_mul_f32_e32 v97, v97, v93
	v_mul_f32_e32 v86, v86, v82
	v_mul_f32_e32 v87, v87, v83
	v_mul_f32_e32 v88, v88, v84
	v_mul_f32_e32 v89, v89, v85
	v_cvt_pk_bf16_f32 v90, v94, v95
	v_cvt_pk_bf16_f32 v91, v96, v97
	v_cvt_pk_bf16_f32 v92, v86, v87
	v_cvt_pk_bf16_f32 v93, v88, v89
	global_store_dwordx4 v172, v[90:93], s[30:31]
	v_add_u32_e32 v172, 0x16000, v172
	v_mul_f32_e32 v78, v74, v78
	v_mul_f32_e32 v79, v75, v79
	v_mul_f32_e32 v80, v76, v80
	v_mul_f32_e32 v81, v77, v81
	v_mul_f32_e32 v70, v66, v70
	v_mul_f32_e32 v71, v67, v71
	v_mul_f32_e32 v72, v68, v72
	v_mul_f32_e32 v73, v69, v73
	v_mul_f32_e32 v74, v235, v74
	v_mul_f32_e32 v75, v235, v75
	v_mul_f32_e32 v76, v235, v76
	v_mul_f32_e32 v77, v235, v77
	v_mul_f32_e32 v66, v235, v66
	v_mul_f32_e32 v67, v235, v67
	v_mul_f32_e32 v68, v235, v68
	v_mul_f32_e32 v69, v235, v69
	v_exp_f32_e32 v74, v74
	v_exp_f32_e32 v75, v75
	v_exp_f32_e32 v76, v76
	v_exp_f32_e32 v77, v77
	v_exp_f32_e32 v66, v66
	v_exp_f32_e32 v67, v67
	v_exp_f32_e32 v68, v68
	v_exp_f32_e32 v69, v69
	v_fma_f32 v74, v74, v234, v234
	v_fma_f32 v75, v75, v234, v234
	v_fma_f32 v76, v76, v234, v234
	v_fma_f32 v77, v77, v234, v234
	v_fma_f32 v66, v66, v234, v234
	v_fma_f32 v67, v67, v234, v234
	v_fma_f32 v68, v68, v234, v234
	v_fma_f32 v69, v69, v234, v234
	v_rcp_f32_e32 v74, v74
	v_rcp_f32_e32 v75, v75
	v_rcp_f32_e32 v76, v76
	v_rcp_f32_e32 v77, v77
	v_rcp_f32_e32 v66, v66
	v_rcp_f32_e32 v67, v67
	v_rcp_f32_e32 v68, v68
	v_rcp_f32_e32 v69, v69
	v_mul_f32_e32 v78, v78, v74
	v_mul_f32_e32 v79, v79, v75
	v_mul_f32_e32 v80, v80, v76
	v_mul_f32_e32 v81, v81, v77
	v_mul_f32_e32 v70, v70, v66
	v_mul_f32_e32 v71, v71, v67
	v_mul_f32_e32 v72, v72, v68
	v_mul_f32_e32 v73, v73, v69
	v_cvt_pk_bf16_f32 v74, v78, v79
	v_cvt_pk_bf16_f32 v75, v80, v81
	v_cvt_pk_bf16_f32 v76, v70, v71
	v_cvt_pk_bf16_f32 v77, v72, v73
	global_store_dwordx4 v172, v[74:77], s[30:31]
	v_add_u32_e32 v172, 0x6e000, v172
	v_mul_f32_e32 v62, v58, v62
	v_mul_f32_e32 v63, v59, v63
	v_mul_f32_e32 v64, v60, v64
	v_mul_f32_e32 v65, v61, v65
	v_mul_f32_e32 v54, v50, v54
	v_mul_f32_e32 v55, v51, v55
	v_mul_f32_e32 v56, v52, v56
	v_mul_f32_e32 v57, v53, v57
	v_mul_f32_e32 v58, v239, v58
	v_mul_f32_e32 v59, v239, v59
	v_mul_f32_e32 v60, v239, v60
	v_mul_f32_e32 v61, v239, v61
	v_mul_f32_e32 v50, v239, v50
	v_mul_f32_e32 v51, v239, v51
	v_mul_f32_e32 v52, v239, v52
	v_mul_f32_e32 v53, v239, v53
	v_exp_f32_e32 v58, v58
	v_exp_f32_e32 v59, v59
	v_exp_f32_e32 v60, v60
	v_exp_f32_e32 v61, v61
	v_exp_f32_e32 v50, v50
	v_exp_f32_e32 v51, v51
	v_exp_f32_e32 v52, v52
	v_exp_f32_e32 v53, v53
	v_fma_f32 v58, v58, v238, v238
	v_fma_f32 v59, v59, v238, v238
	v_fma_f32 v60, v60, v238, v238
	v_fma_f32 v61, v61, v238, v238
	v_fma_f32 v50, v50, v238, v238
	v_fma_f32 v51, v51, v238, v238
	v_fma_f32 v52, v52, v238, v238
	v_fma_f32 v53, v53, v238, v238
	v_rcp_f32_e32 v58, v58
	v_rcp_f32_e32 v59, v59
	v_rcp_f32_e32 v60, v60
	v_rcp_f32_e32 v61, v61
	v_rcp_f32_e32 v50, v50
	v_rcp_f32_e32 v51, v51
	v_rcp_f32_e32 v52, v52
	v_rcp_f32_e32 v53, v53
	v_mul_f32_e32 v62, v62, v58
	v_mul_f32_e32 v63, v63, v59
	v_mul_f32_e32 v64, v64, v60
	v_mul_f32_e32 v65, v65, v61
	v_mul_f32_e32 v54, v54, v50
	v_mul_f32_e32 v55, v55, v51
	v_mul_f32_e32 v56, v56, v52
	v_mul_f32_e32 v57, v57, v53
	v_cvt_pk_bf16_f32 v58, v62, v63
	v_cvt_pk_bf16_f32 v59, v64, v65
	v_cvt_pk_bf16_f32 v60, v54, v55
	v_cvt_pk_bf16_f32 v61, v56, v57
	global_store_dwordx4 v172, v[58:61], s[30:31]
	v_add_u32_e32 v172, 0x16000, v172
	v_mul_f32_e32 v46, v42, v46
	v_mul_f32_e32 v47, v43, v47
	v_mul_f32_e32 v48, v44, v48
	v_mul_f32_e32 v49, v45, v49
	v_mul_f32_e32 v38, v34, v38
	v_mul_f32_e32 v39, v35, v39
	v_mul_f32_e32 v40, v36, v40
	v_mul_f32_e32 v41, v37, v41
	v_mul_f32_e32 v42, v243, v42
	v_mul_f32_e32 v43, v243, v43
	v_mul_f32_e32 v44, v243, v44
	v_mul_f32_e32 v45, v243, v45
	v_mul_f32_e32 v34, v243, v34
	v_mul_f32_e32 v35, v243, v35
	v_mul_f32_e32 v36, v243, v36
; #define PG8_BAR __builtin_amdgcn_s_barrier()
; __device__ __forceinline__ float sigm(float x) { return __builtin_amdgcn_rcpf(1.0f + __expf(-x)); }
; __device__ __forceinline__ u32x4 pack8(f32x4 a, f32x4 b) { u32x4 w; w.x = cvt_pk_bf16(a[0], a[1]); w.y = cvt_pk_bf16(a[2], a[3]); w.z = cvt_pk_bf16(b[0], b[1]); w.w = cvt_pk_bf16(b[2], b[3]); return w; }
; template <class Epi, class Sched, bool ALIGN_EPI = false, bool SP2 = false>
; __device__ __forceinline__ void gemm_phase(PG8_LAS unsigned char* lds, const Gemm g, const Sched& S, const Epi& E) {
;     ...
;         if (!has_next) break;
;         bool keep_acc = false;
;         if constexpr (Epi::KEEP_ACC) keep_acc = E.keep(cur);
;         if constexpr (Epi::KEEP_ACC) { if (!keep_acc) {
; #pragma unroll
;         for (int a = 0; a < 2; ++a)
; #pragma unroll
;             for (int b = 0; b < 2; ++b)
; #pragma unroll
;                 for (int m = 0; m < 4; ++m)
; #pragma unroll
;                     for (int n = 0; n < 2; ++n) acc[a][b][m][n] = (f32x4){0.f, 0.f, 0.f, 0.f};
;         } }
;         cur = nxt; cA = nA; cB = nB; ++ui;
;         if constexpr (ALIGN_EPI) { if (wr == 1) PG8_BAR; }
;     __device__ __forceinline__ void operator()(const f32x4 (&acc)[2][2][4][2], const Unit& u, int wr, int wc, int fr_, int fq_) const {
;     ...
; #pragma unroll
;         for (int ai = 0; ai < 2; ++ai)
; #pragma unroll
;             for (int m = 0; m < 4; ++m) {
;                 const int row = u.pm * 256 + ai * 128 + wr * 64 + m * 16 + fr;
;                 const float rstd = rs8[ai][m];
;                 f32x4 o[2];
; #pragma unroll
;                 for (int n = 0; n < 2; ++n) { const f32x4 g = acc[ai][0][m][n] * rstd, up = acc[ai][1][m][n] * rstd;
; #pragma unroll
;                     for (int i = 0; i < 4; ++i) o[n][i] = g[i] * sigm(g[i]) * up[i]; }
;                 *(u32x4*)(ACT + (size_t)row * DFF + 128 * u.pn + 32 * wc + 8 * fq) = pack8(o[0], o[1]);
	v_mul_f32_e32 v37, v243, v37
	v_exp_f32_e32 v42, v42
	v_exp_f32_e32 v43, v43
	v_exp_f32_e32 v44, v44
	v_exp_f32_e32 v45, v45
	v_exp_f32_e32 v34, v34
	v_exp_f32_e32 v35, v35
	v_exp_f32_e32 v36, v36
	v_exp_f32_e32 v37, v37
	v_fma_f32 v42, v42, v242, v242
	v_fma_f32 v43, v43, v242, v242
	v_fma_f32 v44, v44, v242, v242
	v_fma_f32 v45, v45, v242, v242
	v_fma_f32 v34, v34, v242, v242
	v_fma_f32 v35, v35, v242, v242
	v_fma_f32 v36, v36, v242, v242
	v_fma_f32 v37, v37, v242, v242
	v_rcp_f32_e32 v42, v42
	v_rcp_f32_e32 v43, v43
	v_rcp_f32_e32 v44, v44
	v_rcp_f32_e32 v45, v45
	v_rcp_f32_e32 v34, v34
	v_rcp_f32_e32 v35, v35
	v_rcp_f32_e32 v36, v36
	v_rcp_f32_e32 v37, v37
	v_mul_f32_e32 v46, v46, v42
	v_mul_f32_e32 v47, v47, v43
	v_mul_f32_e32 v48, v48, v44
	v_mul_f32_e32 v49, v49, v45
	v_mul_f32_e32 v38, v38, v34
	v_mul_f32_e32 v39, v39, v35
	v_mul_f32_e32 v40, v40, v36
	v_mul_f32_e32 v41, v41, v37
	v_cvt_pk_bf16_f32 v42, v46, v47
	v_cvt_pk_bf16_f32 v43, v48, v49
	v_cvt_pk_bf16_f32 v44, v38, v39
	v_cvt_pk_bf16_f32 v45, v40, v41
	global_store_dwordx4 v172, v[42:45], s[30:31]
	v_add_u32_e32 v172, 0x16000, v172
	v_mul_f32_e32 v30, v26, v30
	v_mul_f32_e32 v31, v27, v31
	v_mul_f32_e32 v32, v28, v32
	v_mul_f32_e32 v33, v29, v33
	v_mul_f32_e32 v22, v18, v22
	v_mul_f32_e32 v23, v19, v23
	v_mul_f32_e32 v24, v20, v24
	v_mul_f32_e32 v25, v21, v25
	v_mul_f32_e32 v26, v247, v26
	v_mul_f32_e32 v27, v247, v27
	v_mul_f32_e32 v28, v247, v28
	v_mul_f32_e32 v29, v247, v29
	v_mul_f32_e32 v18, v247, v18
	v_mul_f32_e32 v19, v247, v19
	v_mul_f32_e32 v20, v247, v20
	v_mul_f32_e32 v21, v247, v21
	v_exp_f32_e32 v26, v26
	v_exp_f32_e32 v27, v27
	v_exp_f32_e32 v28, v28
	v_exp_f32_e32 v29, v29
	v_exp_f32_e32 v18, v18
	v_exp_f32_e32 v19, v19
	v_exp_f32_e32 v20, v20
	v_exp_f32_e32 v21, v21
	v_fma_f32 v26, v26, v246, v246
	v_fma_f32 v27, v27, v246, v246
	v_fma_f32 v28, v28, v246, v246
	v_fma_f32 v29, v29, v246, v246
	v_fma_f32 v18, v18, v246, v246
	v_fma_f32 v19, v19, v246, v246
	v_fma_f32 v20, v20, v246, v246
	v_fma_f32 v21, v21, v246, v246
	v_rcp_f32_e32 v26, v26
	v_rcp_f32_e32 v27, v27
	v_rcp_f32_e32 v28, v28
	v_rcp_f32_e32 v29, v29
	v_rcp_f32_e32 v18, v18
	v_rcp_f32_e32 v19, v19
	v_rcp_f32_e32 v20, v20
	v_rcp_f32_e32 v21, v21
	v_mul_f32_e32 v30, v30, v26
	v_mul_f32_e32 v31, v31, v27
	v_mul_f32_e32 v32, v32, v28
	v_mul_f32_e32 v33, v33, v29
	v_mul_f32_e32 v22, v22, v18
	v_mul_f32_e32 v23, v23, v19
	v_mul_f32_e32 v24, v24, v20
	v_mul_f32_e32 v25, v25, v21
	v_cvt_pk_bf16_f32 v26, v30, v31
	v_cvt_pk_bf16_f32 v27, v32, v33
	v_cvt_pk_bf16_f32 v28, v22, v23
	v_cvt_pk_bf16_f32 v29, v24, v25
	global_store_dwordx4 v172, v[26:29], s[30:31]
	v_add_u32_e32 v172, 0x16000, v172
	v_mul_f32_e32 v14, v10, v14
	v_mul_f32_e32 v15, v11, v15
	v_mul_f32_e32 v16, v12, v16
	v_mul_f32_e32 v17, v13, v17
	v_mul_f32_e32 v6, v2, v6
	v_mul_f32_e32 v7, v3, v7
	v_mul_f32_e32 v8, v4, v8
	v_mul_f32_e32 v9, v5, v9
	v_mul_f32_e32 v10, v131, v10
	v_mul_f32_e32 v11, v131, v11
	v_mul_f32_e32 v12, v131, v12
	v_mul_f32_e32 v13, v131, v13
	v_mul_f32_e32 v2, v131, v2
	v_mul_f32_e32 v3, v131, v3
	v_mul_f32_e32 v4, v131, v4
	v_mul_f32_e32 v5, v131, v5
	v_exp_f32_e32 v10, v10
	v_exp_f32_e32 v11, v11
	v_exp_f32_e32 v12, v12
	v_exp_f32_e32 v13, v13
	v_exp_f32_e32 v2, v2
	v_exp_f32_e32 v3, v3
	v_exp_f32_e32 v4, v4
	v_exp_f32_e32 v5, v5
	v_fma_f32 v10, v10, v130, v130
	v_fma_f32 v11, v11, v130, v130
	v_fma_f32 v12, v12, v130, v130
	v_fma_f32 v13, v13, v130, v130
	v_fma_f32 v2, v2, v130, v130
	v_fma_f32 v3, v3, v130, v130
	v_fma_f32 v4, v4, v130, v130
	v_fma_f32 v5, v5, v130, v130
	v_rcp_f32_e32 v10, v10
	v_rcp_f32_e32 v11, v11
	v_rcp_f32_e32 v12, v12
	v_rcp_f32_e32 v13, v13
	v_rcp_f32_e32 v2, v2
	v_rcp_f32_e32 v3, v3
	v_rcp_f32_e32 v4, v4
	v_rcp_f32_e32 v5, v5
	v_mul_f32_e32 v14, v14, v10
	v_mul_f32_e32 v15, v15, v11
	v_mul_f32_e32 v16, v16, v12
	v_mul_f32_e32 v17, v17, v13
	v_mul_f32_e32 v6, v6, v2
	v_mul_f32_e32 v7, v7, v3
	v_mul_f32_e32 v8, v8, v4
	v_mul_f32_e32 v9, v9, v5
	v_cvt_pk_bf16_f32 v10, v14, v15
	v_cvt_pk_bf16_f32 v11, v16, v17
	v_cvt_pk_bf16_f32 v12, v6, v7
	v_cvt_pk_bf16_f32 v13, v8, v9
	global_store_dwordx4 v172, v[10:13], s[30:31]
	s_andn2_b64 vcc, exec, s[38:39]
	s_mov_b64 s[0:1], -1
	s_cbranch_vccnz .LBB0_43
	v_readlane_b32 s0, v255, 45
	v_readlane_b32 s1, v255, 46
	s_andn2_b64 vcc, exec, s[0:1]
	s_cbranch_vccnz .LBB0_42
	s_barrier
	s_branch .LBB0_42
